# y1 + attention PV: first V-fragment tr reads issued right after the QK^T MFMAs into spare VGPRs
# baseline (speedup 1.0000x reference)
.LBB0_302:
	v_lshl_add_u64 v[70:71], v[150:151], 0, v[146:147]
	v_add_co_u32_e32 v66, vcc, 0x4da00000, v70
	v_lshl_add_u64 v[82:83], v[148:149], 0, v[146:147]
	s_nop 0
	v_addc_co_u32_e32 v67, vcc, 0, v71, vcc
	v_add_co_u32_e32 v70, vcc, 0x51a00000, v70
	global_load_dwordx4 v[66:69], v[66:67], off
	s_nop 0
	v_addc_co_u32_e32 v71, vcc, 0, v71, vcc
	v_add_co_u32_e32 v74, vcc, 0x4da04000, v82
	global_load_dwordx4 v[70:73], v[70:71], off
	s_nop 0
	v_addc_co_u32_e32 v75, vcc, 0, v83, vcc
	v_add_co_u32_e32 v78, vcc, 0x51a04000, v82
	global_load_dwordx4 v[74:77], v[74:75], off
	s_nop 0
	v_addc_co_u32_e32 v79, vcc, 0, v83, vcc
	v_add_co_u32_e32 v166, vcc, 0x4da08000, v82
	global_load_dwordx4 v[78:81], v[78:79], off
	s_nop 0
	v_addc_co_u32_e32 v167, vcc, 0, v83, vcc
	v_add_co_u32_e32 v170, vcc, 0x51a08000, v82
	global_load_dwordx4 v[166:169], v[166:167], off
	s_nop 0
	v_addc_co_u32_e32 v171, vcc, 0, v83, vcc
	v_add_co_u32_e32 v174, vcc, 0x4da0c000, v82
	global_load_dwordx4 v[170:173], v[170:171], off
	s_nop 0
	v_addc_co_u32_e32 v175, vcc, 0, v83, vcc
	v_add_co_u32_e32 v178, vcc, 0x51a0c000, v82
	global_load_dwordx4 v[174:177], v[174:175], off
	s_nop 0
	v_addc_co_u32_e32 v179, vcc, 0, v83, vcc
	v_add_co_u32_e32 v182, vcc, 0x4da10000, v82
	global_load_dwordx4 v[178:181], v[178:179], off
	s_nop 0
	v_addc_co_u32_e32 v183, vcc, 0, v83, vcc
	v_add_co_u32_e32 v188, vcc, 0x51a10000, v82
	global_load_dwordx4 v[182:185], v[182:183], off
	s_nop 0
	v_addc_co_u32_e32 v189, vcc, 0, v83, vcc
	v_add_co_u32_e32 v192, vcc, 0x4da14000, v82
	global_load_dwordx4 v[188:191], v[188:189], off
	s_nop 0
	v_addc_co_u32_e32 v193, vcc, 0, v83, vcc
	v_add_co_u32_e32 v196, vcc, 0x51a14000, v82
	global_load_dwordx4 v[192:195], v[192:193], off
	s_nop 0
	v_addc_co_u32_e32 v197, vcc, 0, v83, vcc
	v_add_co_u32_e32 v200, vcc, 0x4da18000, v82
	global_load_dwordx4 v[196:199], v[196:197], off
	s_nop 0
	v_addc_co_u32_e32 v201, vcc, 0, v83, vcc
	v_add_co_u32_e32 v204, vcc, 0x51a18000, v82
	global_load_dwordx4 v[200:203], v[200:201], off
	s_nop 0
	v_addc_co_u32_e32 v205, vcc, 0, v83, vcc
	v_add_co_u32_e32 v208, vcc, 0x4da1c000, v82
	global_load_dwordx4 v[204:207], v[204:205], off
	s_nop 0
	v_addc_co_u32_e32 v209, vcc, 0, v83, vcc
	v_add_co_u32_e32 v82, vcc, 0x51a1c000, v82
	global_load_dwordx4 v[208:211], v[208:209], off
	s_nop 0
	v_addc_co_u32_e32 v83, vcc, 0, v83, vcc
	global_load_dwordx4 v[212:215], v[82:83], off
	s_waitcnt lgkmcnt(0)
	v_lshl_add_u64 v[148:149], v[148:149], 0, s[92:93]
	v_lshl_add_u64 v[150:151], v[150:151], 0, s[92:93]
	s_waitcnt vmcnt(15)
	ds_write_b128 v162, v[66:69]
	s_waitcnt vmcnt(14)
	ds_write_b128 v162, v[70:73] offset:8704
	s_waitcnt vmcnt(13)
	ds_write_b128 v162, v[74:77] offset:1088
	s_waitcnt vmcnt(12)
	ds_write_b128 v162, v[78:81] offset:9792
	s_waitcnt vmcnt(11)
	ds_write_b128 v162, v[166:169] offset:2176
	s_waitcnt vmcnt(10)
	ds_write_b128 v162, v[170:173] offset:10880
	s_waitcnt vmcnt(9)
	ds_write_b128 v162, v[174:177] offset:3264
	s_waitcnt vmcnt(8)
	ds_write_b128 v162, v[178:181] offset:11968
	s_waitcnt vmcnt(7)
	ds_write_b128 v162, v[182:185] offset:4352
	s_waitcnt vmcnt(6)
	ds_write_b128 v162, v[188:191] offset:13056
	s_waitcnt vmcnt(5)
	ds_write_b128 v162, v[192:195] offset:5440
	s_waitcnt vmcnt(4)
	ds_write_b128 v162, v[196:199] offset:14144
	s_waitcnt vmcnt(3)
	ds_write_b128 v162, v[200:203] offset:6528
	s_waitcnt vmcnt(2)
	ds_write_b128 v162, v[204:207] offset:15232
	s_waitcnt vmcnt(1)
	ds_write_b128 v162, v[208:211] offset:7616
	s_waitcnt vmcnt(0)
	ds_write_b128 v162, v[212:215] offset:16320
	s_waitcnt lgkmcnt(0)
	ds_read_b128 v[66:69], v163
	ds_read_b128 v[166:169], v163 offset:32
	ds_read_b128 v[216:219], v163 offset:64
	ds_read_b128 v[220:223], v163 offset:96
	ds_read_b128 v[242:245], v163 offset:128
	s_waitcnt lgkmcnt(4)
	v_mfma_f32_32x32x16_bf16 v[66:81], v[66:69], v[92:95], 0
	s_waitcnt lgkmcnt(3)
	v_mfma_f32_32x32x16_bf16 v[66:81], v[166:169], v[96:99], v[66:81]
	ds_read_b128 v[166:169], v163 offset:160
	s_waitcnt lgkmcnt(3)
	v_mfma_f32_32x32x16_bf16 v[66:81], v[216:219], v[100:103], v[66:81]
	ds_read_b128 v[216:219], v163 offset:192
	s_waitcnt lgkmcnt(3)
	v_mfma_f32_32x32x16_bf16 v[66:81], v[220:223], v[104:107], v[66:81]
	ds_read_b128 v[220:223], v163 offset:224
	s_waitcnt lgkmcnt(3)
	v_mfma_f32_32x32x16_bf16 v[66:81], v[242:245], v[108:111], v[66:81]
	s_waitcnt lgkmcnt(2)
	v_mfma_f32_32x32x16_bf16 v[66:81], v[166:169], v[112:115], v[66:81]
	s_waitcnt lgkmcnt(1)
	v_mfma_f32_32x32x16_bf16 v[66:81], v[216:219], v[120:123], v[66:81]
	s_waitcnt lgkmcnt(0)
	v_mfma_f32_32x32x16_bf16 v[66:81], v[220:223], v[116:119], v[66:81]
	ds_read_b64_tr_b16 v[216:217], v131
	ds_read_b64_tr_b16 v[218:219], v133
	ds_read_b64_tr_b16 v[220:221], v135
	ds_read_b64_tr_b16 v[222:223], v137
	ds_read_b64_tr_b16 v[242:243], v139
	ds_read_b64_tr_b16 v[244:245], v141
	s_nop 11
	v_exp_f32_e64 v1, -|v66|
	v_max_f32_e32 v165, v69, v69
	v_min_f32_e32 v165, 0, v165
	v_add_f32_e32 v1, 1.0, v1
	v_log_f32_e32 v170, v1
	v_max_f32_e64 v1, -v66, -v66
	v_min_f32_e32 v82, 0, v1
	v_exp_f32_e64 v1, -|v67|
	v_max_f32_e32 v66, v66, v66
	v_min_f32_e32 v66, 0, v66
	v_sub_f32_e32 v66, v66, v170
	v_add_f32_e32 v1, 1.0, v1
	v_log_f32_e32 v171, v1
	v_max_f32_e32 v1, v67, v67
	v_max_f32_e64 v67, -v67, -v67
	v_min_f32_e32 v83, 0, v67
	v_pk_add_f32 v[172:173], v[82:83], v[170:171] neg_lo:[0,1] neg_hi:[0,1]
	v_exp_f32_e64 v67, -|v68|
	v_exp_f32_e64 v83, -|v69|
	v_max_f32_e64 v69, -v69, -v69
	v_min_f32_e32 v69, 0, v69
	v_add_f32_e32 v67, 1.0, v67
	v_add_f32_e32 v83, 1.0, v83
	v_log_f32_e32 v82, v67
	v_log_f32_e32 v83, v83
	v_max_f32_e32 v67, v68, v68
	v_max_f32_e64 v68, -v68, -v68
	v_min_f32_e32 v68, 0, v68
	v_pk_add_f32 v[174:175], v[68:69], v[82:83] neg_lo:[0,1] neg_hi:[0,1]
	v_exp_f32_e64 v68, -|v70|
	v_sub_f32_e32 v165, v165, v83
	v_min_f32_e32 v67, 0, v67
	v_sub_f32_e32 v67, v67, v82
	v_add_f32_e32 v68, 1.0, v68
	v_log_f32_e32 v69, v68
	v_max_f32_e32 v68, v70, v70
	v_min_f32_e32 v166, 0, v68
	v_max_f32_e64 v68, -v70, -v70
	v_min_f32_e32 v83, 0, v68
	v_exp_f32_e64 v68, -|v71|
	v_max_f32_e32 v70, v71, v71
	v_max_f32_e64 v71, -v71, -v71
	v_min_f32_e32 v70, 0, v70
	v_add_f32_e32 v68, 1.0, v68
	v_log_f32_e32 v68, v68
	v_min_f32_e32 v82, 0, v71
	v_min_f32_e32 v1, 0, v1
	v_sub_f32_e32 v1, v1, v171
	v_sub_f32_e32 v192, v70, v68
	v_pk_add_f32 v[176:177], v[82:83], v[68:69] neg_lo:[0,1] neg_hi:[0,1]
	v_exp_f32_e64 v68, -|v72|
	v_sub_f32_e32 v171, v166, v69
	v_max_f32_e32 v70, v73, v73
	v_add_f32_e32 v68, 1.0, v68
	v_log_f32_e32 v69, v68
	v_max_f32_e32 v68, v72, v72
	v_min_f32_e32 v82, 0, v68
	v_max_f32_e64 v68, -v72, -v72
	v_min_f32_e32 v71, 0, v68
	v_exp_f32_e64 v68, -|v73|
	v_min_f32_e32 v72, 0, v70
	v_max_f32_e64 v70, -v73, -v73
	v_min_f32_e32 v70, 0, v70
	v_add_f32_e32 v68, 1.0, v68
	v_log_f32_e32 v68, v68
	v_sub_f32_e32 v193, v82, v69
	v_sub_f32_e32 v194, v72, v68
	v_pk_add_f32 v[178:179], v[70:71], v[68:69] neg_lo:[0,1] neg_hi:[0,1]
	v_exp_f32_e64 v68, -|v74|
	v_max_f32_e32 v70, v75, v75
	v_min_f32_e32 v73, 0, v70
	v_max_f32_e64 v70, -v75, -v75
	v_add_f32_e32 v68, 1.0, v68
	v_log_f32_e32 v69, v68
	v_max_f32_e32 v68, v74, v74
	v_min_f32_e32 v72, 0, v68
	v_max_f32_e64 v68, -v74, -v74
	v_min_f32_e32 v71, 0, v68
	v_exp_f32_e64 v68, -|v75|
	v_min_f32_e32 v70, 0, v70
	v_sub_f32_e32 v195, v72, v69
	v_add_f32_e32 v68, 1.0, v68
	v_log_f32_e32 v68, v68
	s_nop 0
	v_sub_f32_e32 v196, v73, v68
	v_pk_add_f32 v[180:181], v[70:71], v[68:69] neg_lo:[0,1] neg_hi:[0,1]
	v_exp_f32_e64 v68, -|v76|
	v_max_f32_e32 v70, v77, v77
	v_min_f32_e32 v73, 0, v70
	v_max_f32_e64 v70, -v77, -v77
	v_add_f32_e32 v68, 1.0, v68
	v_log_f32_e32 v69, v68
	v_max_f32_e32 v68, v76, v76
	v_min_f32_e32 v72, 0, v68
	v_max_f32_e64 v68, -v76, -v76
	v_min_f32_e32 v71, 0, v68
	v_exp_f32_e64 v68, -|v77|
	v_min_f32_e32 v70, 0, v70
	v_sub_f32_e32 v197, v72, v69
	v_pk_mov_b32 v[166:167], v[180:181], v[180:181] op_sel:[1,0]
	v_add_f32_e32 v68, 1.0, v68
	v_log_f32_e32 v68, v68
	v_cvt_pk_bf16_f32 v166, v166, v167
	v_sub_f32_e32 v198, v73, v68
	v_pk_add_f32 v[182:183], v[70:71], v[68:69] neg_lo:[0,1] neg_hi:[0,1]
	v_exp_f32_e64 v68, -|v78|
	v_max_f32_e32 v70, v79, v79
	v_min_f32_e32 v73, 0, v70
	v_max_f32_e64 v70, -v79, -v79
	v_add_f32_e32 v68, 1.0, v68
	v_log_f32_e32 v69, v68
	v_max_f32_e32 v68, v78, v78
	v_min_f32_e32 v72, 0, v68
	v_max_f32_e64 v68, -v78, -v78
	v_min_f32_e32 v71, 0, v68
	v_exp_f32_e64 v68, -|v79|
	v_min_f32_e32 v70, 0, v70
	v_sub_f32_e32 v199, v72, v69
	v_pk_mov_b32 v[168:169], v[182:183], v[182:183] op_sel:[1,0]
	v_add_f32_e32 v68, 1.0, v68
	v_log_f32_e32 v68, v68
	v_cvt_pk_bf16_f32 v167, v168, v169
	v_sub_f32_e32 v200, v73, v68
	v_pk_add_f32 v[184:185], v[70:71], v[68:69] neg_lo:[0,1] neg_hi:[0,1]
	v_exp_f32_e64 v68, -|v80|
	v_max_f32_e32 v70, v81, v81
	v_min_f32_e32 v73, 0, v70
	v_max_f32_e64 v70, -v81, -v81
	v_add_f32_e32 v68, 1.0, v68
	v_log_f32_e32 v69, v68
	v_max_f32_e32 v68, v80, v80
	v_min_f32_e32 v72, 0, v68
	v_max_f32_e64 v68, -v80, -v80
	v_min_f32_e32 v71, 0, v68
	v_exp_f32_e64 v68, -|v81|
	v_min_f32_e32 v70, 0, v70
	v_sub_f32_e32 v201, v72, v69
	v_pk_mov_b32 v[168:169], v[184:185], v[184:185] op_sel:[1,0]
	v_add_f32_e32 v68, 1.0, v68
	v_log_f32_e32 v68, v68
	v_cvt_pk_bf16_f32 v168, v168, v169
	v_sub_f32_e32 v202, v73, v68
	v_pk_add_f32 v[188:189], v[70:71], v[68:69] neg_lo:[0,1] neg_hi:[0,1]
	v_pk_mov_b32 v[70:71], v[176:177], v[176:177] op_sel:[1,0]
	v_pk_mov_b32 v[72:73], v[178:179], v[178:179] op_sel:[1,0]
	v_cvt_pk_bf16_f32 v68, v172, v173
	v_cvt_pk_bf16_f32 v69, v174, v175
	v_cvt_pk_bf16_f32 v70, v70, v71
	v_cvt_pk_bf16_f32 v71, v72, v73
	v_pk_mov_b32 v[190:191], v[188:189], v[188:189] op_sel:[1,0]
	s_nop 0
	v_mfma_f32_32x32x16_bf16 v[68:83], v[84:87], v[68:71], 0
	v_cvt_pk_bf16_f32 v169, v190, v191
	s_nop 1
	v_mfma_f32_32x32x16_bf16 v[68:83], v[88:91], v[166:169], v[68:83]
	v_add_f32_e32 v166, 0, v172
	v_add_f32_e32 v166, v173, v166
	v_add_f32_e32 v166, v174, v166
	v_add_f32_e32 v166, v175, v166
	v_add_f32_e32 v166, v177, v166
	v_add_f32_e32 v166, v176, v166
	v_add_f32_e32 v166, v179, v166
	s_nop 4
	v_add_f32_e32 v67, v70, v67
	v_add_f32_e32 v70, v73, v192
	v_add_f32_e32 v73, v76, v195
	v_add_f32_e32 v73, v164, v73
	v_add_f32_e32 v66, v68, v66
	v_add_f32_e32 v68, v71, v165
	v_exp_f32_e32 v165, v73
	v_add_f32_e32 v73, v77, v196
	v_add_f32_e32 v73, v164, v73
	v_exp_f32_e32 v170, v73
	v_add_f32_e32 v73, v78, v197
	v_add_f32_e32 v73, v164, v73
	v_add_f32_e32 v1, v69, v1
	v_add_f32_e32 v69, v72, v171
	v_exp_f32_e32 v171, v73
	v_add_f32_e32 v73, v79, v198
	v_add_f32_e32 v73, v164, v73
	v_add_f32_e32 v166, v178, v166
	v_exp_f32_e32 v172, v73
	v_add_f32_e32 v73, v80, v199
	v_add_f32_e32 v166, v181, v166
	v_add_f32_e32 v73, v164, v73
	v_add_f32_e32 v166, v180, v166
	v_exp_f32_e32 v173, v73
	v_add_f32_e32 v73, v81, v200
	v_add_f32_e32 v166, v183, v166
	v_add_f32_e32 v73, v164, v73
	v_add_f32_e32 v166, v182, v166
	v_exp_f32_e32 v174, v73
	v_add_f32_e32 v73, v82, v201
	v_add_f32_e32 v166, v185, v166
	v_add_f32_e32 v73, v164, v73
	v_add_f32_e32 v166, v184, v166
	v_exp_f32_e32 v82, v73
	v_add_f32_e32 v73, v83, v202
	v_add_f32_e32 v166, v189, v166
	v_add_f32_e32 v73, v164, v73
	v_add_f32_e32 v71, v74, v193
	v_add_f32_e32 v72, v75, v194
	v_exp_f32_e32 v83, v73
	v_add_f32_e32 v73, v188, v166
	v_add_f32_e32 v66, v164, v66
	v_add_f32_e32 v1, v164, v1
	v_add_f32_e32 v67, v164, v67
	v_add_f32_e32 v68, v164, v68
	v_add_f32_e32 v69, v164, v69
	v_add_f32_e32 v70, v164, v70
	v_add_f32_e32 v71, v164, v71
	v_add_f32_e32 v72, v164, v72
	ds_bpermute_b32 v74, v145, v73
	v_exp_f32_e32 v66, v66
	v_exp_f32_e32 v1, v1
	v_exp_f32_e32 v67, v67
	v_exp_f32_e32 v68, v68
	v_exp_f32_e32 v69, v69
	v_exp_f32_e32 v70, v70
	v_exp_f32_e32 v71, v71
	v_exp_f32_e32 v72, v72
	s_waitcnt lgkmcnt(0)
	v_add_f32_e32 v175, v73, v74
	v_cvt_pk_bf16_f32 v66, v66, v1
	v_cvt_pk_bf16_f32 v67, v67, v68
	v_cvt_pk_bf16_f32 v68, v69, v70
	v_cvt_pk_bf16_f32 v69, v71, v72
	ds_read_b64_tr_b16 v[78:79], v152
	ds_read_b64_tr_b16 v[80:81], v153
	s_waitcnt lgkmcnt(0)
	v_add_f32_e32 v164, v164, v175
	v_cmp_gt_f32_e32 vcc, s73, v164
	v_mfma_f32_32x32x16_bf16 v[50:65], v[216:219], v[66:69], v[50:65]
	s_cmp_lg_u64 vcc, exec
	s_cselect_b64 s[12:13], -1, 0
	s_cmp_lg_u32 s10, 0
	s_cselect_b64 s[14:15], -1, 0
	s_and_b64 vcc, s[14:15], s[12:13]
	s_add_i32 s10, s10, 1
	s_and_b64 vcc, exec, vcc
	v_mfma_f32_32x32x16_bf16 v[34:49], v[220:223], v[66:69], v[34:49]
	ds_read_b64_tr_b16 v[74:75], v154
	ds_read_b64_tr_b16 v[76:77], v155
	ds_read_b64_tr_b16 v[70:71], v156
	ds_read_b64_tr_b16 v[72:73], v157
	s_waitcnt lgkmcnt(0)
	v_mfma_f32_32x32x16_bf16 v[18:33], v[242:245], v[66:69], v[18:33]
	v_mfma_f32_32x32x16_bf16 v[2:17], v[78:81], v[66:69], v[2:17]
	v_cvt_pk_bf16_f32 v66, v165, v170
	v_cvt_pk_bf16_f32 v67, v171, v172
	v_cvt_pk_bf16_f32 v68, v173, v174
	v_cvt_pk_bf16_f32 v69, v82, v83
	ds_read_b64_tr_b16 v[166:167], v158
	ds_read_b64_tr_b16 v[168:169], v159
	ds_read_b64_tr_b16 v[78:79], v160
	ds_read_b64_tr_b16 v[80:81], v161
	s_waitcnt lgkmcnt(0)
	s_nop 1
	v_mfma_f32_32x32x16_bf16 v[50:65], v[74:77], v[66:69], v[50:65]
	v_mfma_f32_32x32x16_bf16 v[34:49], v[70:73], v[66:69], v[34:49]
	v_mfma_f32_32x32x16_bf16 v[18:33], v[166:169], v[66:69], v[18:33]
	v_mfma_f32_32x32x16_bf16 v[2:17], v[78:81], v[66:69], v[2:17]
	s_cbranch_vccnz .LBB0_302
	s_branch .LBB0_299
